# f_a tile version with every GEMM K-loop head placed at its original byte offset modulo 64
# speedup vs baseline: 1.0126x; 1.0126x over previous
; template <class Epi, class Sched, bool ALIGN_EPI = false, bool SP2 = false>
; __device__ __forceinline__ void gemm_phase(PG8_LAS unsigned char* lds, const Gemm g, const Sched& S, const Epi& E, const int tid_arg) {
;     ...
;         const bool has_next = S.next(ui + 1, nxt);
;         const char* nA = has_next ? (const char*)g.A + (size_t)nxt.pm * tstep : cA; const char* nB = has_next ? (const char*)g.Bt + (size_t)nxt.pn * tstep : cB;
;     ...
; #pragma unroll
;         for (int a = 0; a < 2; ++a)
; #pragma unroll
;             for (int b = 0; b < 2; ++b)
; #pragma unroll
;                 for (int m = 0; m < 4; ++m)
; #pragma unroll
;                     for (int n = 0; n < 2; ++n) acc[a][b][m][n] = (f32x4){0.f, 0.f, 0.f, 0.f};
;         cur = nxt; cA = nA; cB = nB; ++ui;
.LBB0_95:
	s_ashr_i32 s21, s20, 31
	s_lshl_b64 s[22:23], s[20:21], 19
	s_add_u32 s22, s1, s22
	s_addc_u32 s23, s2, s23
	s_and_b64 s[24:25], s[6:7], exec
	s_cselect_b32 s21, s23, s29
	s_cselect_b32 s45, s22, s28
	s_ashr_i32 s19, s18, 31
	s_lshl_b64 s[24:25], s[18:19], 19
	s_add_u32 s24, s12, s24
	s_addc_u32 s25, s13, s25
	s_and_b64 s[34:35], s[6:7], exec
	s_cselect_b32 s19, s25, s31
	s_cselect_b32 s46, s24, s30
	s_add_u32 s28, s28, 0x40080
	s_addc_u32 s29, s29, 0
	s_add_u32 s47, s30, 0x100
	v_mov_b32_e32 v2, 0
	s_addc_u32 s48, s31, 0
	s_mov_b32 s49, -2
	v_mov_b32_e32 v3, v2
	v_mov_b32_e32 v4, v2
	v_mov_b32_e32 v5, v2
	v_mov_b32_e32 v6, v2
	v_mov_b32_e32 v7, v2
	v_mov_b32_e32 v8, v2
	v_mov_b32_e32 v9, v2
	v_mov_b32_e32 v18, v2
	v_mov_b32_e32 v19, v2
	v_mov_b32_e32 v20, v2
	v_mov_b32_e32 v21, v2
	v_mov_b32_e32 v22, v2
	v_mov_b32_e32 v23, v2
	v_mov_b32_e32 v24, v2
	v_mov_b32_e32 v25, v2
	v_mov_b32_e32 v34, v2
	v_mov_b32_e32 v35, v2
	v_mov_b32_e32 v36, v2
	v_mov_b32_e32 v37, v2
	v_mov_b32_e32 v38, v2
	v_mov_b32_e32 v39, v2
	v_mov_b32_e32 v40, v2
	v_mov_b32_e32 v41, v2
	v_mov_b32_e32 v50, v2
	v_mov_b32_e32 v51, v2
	v_mov_b32_e32 v52, v2
	v_mov_b32_e32 v53, v2
	v_mov_b32_e32 v54, v2
	v_mov_b32_e32 v55, v2
	v_mov_b32_e32 v56, v2
	v_mov_b32_e32 v57, v2
	v_mov_b32_e32 v10, v2
	v_mov_b32_e32 v11, v2
	v_mov_b32_e32 v12, v2
	v_mov_b32_e32 v13, v2
	v_mov_b32_e32 v14, v2
	v_mov_b32_e32 v15, v2
	v_mov_b32_e32 v16, v2
	v_mov_b32_e32 v17, v2
	v_mov_b32_e32 v26, v2
	v_mov_b32_e32 v27, v2
	v_mov_b32_e32 v28, v2
	v_mov_b32_e32 v29, v2
	v_mov_b32_e32 v30, v2
	v_mov_b32_e32 v31, v2
	v_mov_b32_e32 v32, v2
	v_mov_b32_e32 v33, v2
	v_mov_b32_e32 v42, v2
	v_mov_b32_e32 v43, v2
	v_mov_b32_e32 v44, v2
	v_mov_b32_e32 v45, v2
	v_mov_b32_e32 v46, v2
	v_mov_b32_e32 v47, v2
	v_mov_b32_e32 v48, v2
	v_mov_b32_e32 v49, v2
	v_mov_b32_e32 v58, v2
	v_mov_b32_e32 v59, v2
	v_mov_b32_e32 v60, v2
	v_mov_b32_e32 v61, v2
	v_mov_b32_e32 v62, v2
	v_mov_b32_e32 v63, v2
	v_mov_b32_e32 v64, v2
	v_mov_b32_e32 v65, v2
	v_mov_b32_e32 v66, v2
	v_mov_b32_e32 v67, v2
	v_mov_b32_e32 v68, v2
	v_mov_b32_e32 v69, v2
	v_mov_b32_e32 v70, v2
	v_mov_b32_e32 v71, v2
	v_mov_b32_e32 v72, v2
	v_mov_b32_e32 v73, v2
	v_mov_b32_e32 v82, v2
	v_mov_b32_e32 v83, v2
	v_mov_b32_e32 v84, v2
	v_mov_b32_e32 v85, v2
	v_mov_b32_e32 v86, v2
	v_mov_b32_e32 v87, v2
	v_mov_b32_e32 v88, v2
	v_mov_b32_e32 v89, v2
	v_mov_b32_e32 v98, v2
	v_mov_b32_e32 v99, v2
	v_mov_b32_e32 v100, v2
	v_mov_b32_e32 v101, v2
	v_mov_b32_e32 v102, v2
	v_mov_b32_e32 v103, v2
	v_mov_b32_e32 v104, v2
	v_mov_b32_e32 v105, v2
	v_mov_b32_e32 v114, v2
	v_mov_b32_e32 v115, v2
	v_mov_b32_e32 v116, v2
	v_mov_b32_e32 v117, v2
	v_mov_b32_e32 v118, v2
	v_mov_b32_e32 v119, v2
	v_mov_b32_e32 v120, v2
	v_mov_b32_e32 v121, v2
	v_mov_b32_e32 v74, v2
	v_mov_b32_e32 v75, v2
	v_mov_b32_e32 v76, v2
	v_mov_b32_e32 v77, v2
	v_mov_b32_e32 v78, v2
	v_mov_b32_e32 v79, v2
	v_mov_b32_e32 v80, v2
	v_mov_b32_e32 v81, v2
	v_mov_b32_e32 v90, v2
	v_mov_b32_e32 v91, v2
	v_mov_b32_e32 v92, v2
	v_mov_b32_e32 v93, v2
	v_mov_b32_e32 v94, v2
	v_mov_b32_e32 v95, v2
	v_mov_b32_e32 v96, v2
	v_mov_b32_e32 v97, v2
	v_mov_b32_e32 v106, v2
	v_mov_b32_e32 v107, v2
	v_mov_b32_e32 v108, v2
	v_mov_b32_e32 v109, v2
	v_mov_b32_e32 v110, v2
	v_mov_b32_e32 v111, v2
	v_mov_b32_e32 v112, v2
	v_mov_b32_e32 v113, v2
	v_mov_b32_e32 v122, v2
	v_mov_b32_e32 v123, v2
	v_mov_b32_e32 v124, v2
	v_mov_b32_e32 v125, v2
	v_mov_b32_e32 v126, v2
	v_mov_b32_e32 v127, v2
	v_mov_b32_e32 v128, v2
	v_mov_b32_e32 v129, v2
	.p2align 6

; template <class Epi, class Sched, bool ALIGN_EPI = false, bool SP2 = false>
; __device__ __forceinline__ void gemm_phase(PG8_LAS unsigned char* lds, const Gemm g, const Sched& S, const Epi& E, const int tid_arg) {
;     ...
; #pragma unroll
;         for (int a = 0; a < 2; ++a)
; #pragma unroll
;             for (int b = 0; b < 2; ++b)
; #pragma unroll
;                 for (int m = 0; m < 4; ++m)
; #pragma unroll
;                     for (int n = 0; n < 2; ++n) acc[a][b][m][n] = (f32x4){0.f, 0.f, 0.f, 0.f};
;         cur = nxt; cA = nA; cB = nB; ++ui;
.LBB0_259:
	s_add_u32 s16, s36, 0x100
	v_mov_b32_e32 v2, 0
	s_addc_u32 s31, s37, 0
	s_mov_b32 s56, -2
	s_waitcnt lgkmcnt(0)
	v_mov_b32_e32 v3, v2
	v_mov_b32_e32 v4, v2
	v_mov_b32_e32 v5, v2
	v_mov_b32_e32 v6, v2
	v_mov_b32_e32 v7, v2
	v_mov_b32_e32 v8, v2
	v_mov_b32_e32 v9, v2
	v_mov_b32_e32 v18, v2
	v_mov_b32_e32 v19, v2
	v_mov_b32_e32 v20, v2
	v_mov_b32_e32 v21, v2
	v_mov_b32_e32 v22, v2
	v_mov_b32_e32 v23, v2
	v_mov_b32_e32 v24, v2
	v_mov_b32_e32 v25, v2
	v_mov_b32_e32 v34, v2
	v_mov_b32_e32 v35, v2
	v_mov_b32_e32 v36, v2
	v_mov_b32_e32 v37, v2
	v_mov_b32_e32 v38, v2
	v_mov_b32_e32 v39, v2
	v_mov_b32_e32 v40, v2
	v_mov_b32_e32 v41, v2
	v_mov_b32_e32 v50, v2
	v_mov_b32_e32 v51, v2
	v_mov_b32_e32 v52, v2
	v_mov_b32_e32 v53, v2
	v_mov_b32_e32 v54, v2
	v_mov_b32_e32 v55, v2
	v_mov_b32_e32 v56, v2
	v_mov_b32_e32 v57, v2
	v_mov_b32_e32 v10, v2
	v_mov_b32_e32 v11, v2
	v_mov_b32_e32 v12, v2
	v_mov_b32_e32 v13, v2
	v_mov_b32_e32 v14, v2
	v_mov_b32_e32 v15, v2
	v_mov_b32_e32 v16, v2
	v_mov_b32_e32 v17, v2
	v_mov_b32_e32 v26, v2
	v_mov_b32_e32 v27, v2
	v_mov_b32_e32 v28, v2
	v_mov_b32_e32 v29, v2
	v_mov_b32_e32 v30, v2
	v_mov_b32_e32 v31, v2
	v_mov_b32_e32 v32, v2
	v_mov_b32_e32 v33, v2
	v_mov_b32_e32 v42, v2
	v_mov_b32_e32 v43, v2
	v_mov_b32_e32 v44, v2
	v_mov_b32_e32 v45, v2
	v_mov_b32_e32 v46, v2
	v_mov_b32_e32 v47, v2
	v_mov_b32_e32 v48, v2
	v_mov_b32_e32 v49, v2
	v_mov_b32_e32 v58, v2
	v_mov_b32_e32 v59, v2
	v_mov_b32_e32 v60, v2
	v_mov_b32_e32 v61, v2
	v_mov_b32_e32 v62, v2
	v_mov_b32_e32 v63, v2
	v_mov_b32_e32 v64, v2
	v_mov_b32_e32 v65, v2
	v_mov_b32_e32 v66, v2
	v_mov_b32_e32 v67, v2
	v_mov_b32_e32 v68, v2
	v_mov_b32_e32 v69, v2
	v_mov_b32_e32 v70, v2
	v_mov_b32_e32 v71, v2
	v_mov_b32_e32 v72, v2
	v_mov_b32_e32 v73, v2
	v_mov_b32_e32 v82, v2
	v_mov_b32_e32 v83, v2
	v_mov_b32_e32 v84, v2
	v_mov_b32_e32 v85, v2
	v_mov_b32_e32 v86, v2
	v_mov_b32_e32 v87, v2
	v_mov_b32_e32 v88, v2
	v_mov_b32_e32 v89, v2
	v_mov_b32_e32 v98, v2
	v_mov_b32_e32 v99, v2
	v_mov_b32_e32 v100, v2
	v_mov_b32_e32 v101, v2
	v_mov_b32_e32 v102, v2
	v_mov_b32_e32 v103, v2
	v_mov_b32_e32 v104, v2
	v_mov_b32_e32 v105, v2
	v_mov_b32_e32 v114, v2
	v_mov_b32_e32 v115, v2
	v_mov_b32_e32 v116, v2
	v_mov_b32_e32 v117, v2
	v_mov_b32_e32 v118, v2
	v_mov_b32_e32 v119, v2
	v_mov_b32_e32 v120, v2
	v_mov_b32_e32 v121, v2
	v_mov_b32_e32 v74, v2
	v_mov_b32_e32 v75, v2
	v_mov_b32_e32 v76, v2
	v_mov_b32_e32 v77, v2
	v_mov_b32_e32 v78, v2
	v_mov_b32_e32 v79, v2
	v_mov_b32_e32 v80, v2
	v_mov_b32_e32 v81, v2
	v_mov_b32_e32 v90, v2
	v_mov_b32_e32 v91, v2
	v_mov_b32_e32 v92, v2
	v_mov_b32_e32 v93, v2
	v_mov_b32_e32 v94, v2
	v_mov_b32_e32 v95, v2
	v_mov_b32_e32 v96, v2
	v_mov_b32_e32 v97, v2
	v_mov_b32_e32 v106, v2
	v_mov_b32_e32 v107, v2
	v_mov_b32_e32 v108, v2
	v_mov_b32_e32 v109, v2
	v_mov_b32_e32 v110, v2
	v_mov_b32_e32 v111, v2
	v_mov_b32_e32 v112, v2
	v_mov_b32_e32 v113, v2
	v_mov_b32_e32 v122, v2
	v_mov_b32_e32 v123, v2
	v_mov_b32_e32 v124, v2
	v_mov_b32_e32 v125, v2
	v_mov_b32_e32 v126, v2
	v_mov_b32_e32 v127, v2
	v_mov_b32_e32 v128, v2
	v_mov_b32_e32 v129, v2
	.p2align 6
	s_nop 0
	s_nop 0
	s_nop 0
	s_nop 0
	s_nop 0
	s_nop 0
	s_nop 0
	s_nop 0

; template <class Epi, class Sched, bool ALIGN_EPI = false, bool SP2 = false>
; __device__ __forceinline__ void gemm_phase(PG8_LAS unsigned char* lds, const Gemm g, const Sched& S, const Epi& E, const int tid_arg) {
;     ...
;         const bool has_next = S.next(ui + 1, nxt);
;         const char* nA = has_next ? (const char*)g.A + (size_t)nxt.pm * tstep : cA; const char* nB = has_next ? (const char*)g.Bt + (size_t)nxt.pn * tstep : cB;
;         for (int t = 0; t < nt; t += 2) {
;             const bool last = (t == nt - 2);
;     ...
; #pragma unroll
;         for (int a = 0; a < 2; ++a)
; #pragma unroll
;             for (int b = 0; b < 2; ++b)
; #pragma unroll
;                 for (int m = 0; m < 4; ++m)
; #pragma unroll
;                     for (int n = 0; n < 2; ++n) acc[a][b][m][n] = (f32x4){0.f, 0.f, 0.f, 0.f};
;         cur = nxt; cA = nA; cB = nB; ++ui;
.LBB0_362:
	s_ashr_i32 s29, s28, 31
	s_lshl_b64 s[6:7], s[28:29], 19
	s_add_u32 s30, s50, s6
	s_addc_u32 s31, s51, s7
	s_and_b64 s[6:7], s[8:9], exec
	s_cselect_b32 s6, s31, s15
	s_cselect_b32 s7, s30, s14
	s_ashr_i32 s27, s26, 31
	s_lshl_b64 s[34:35], s[26:27], 19
	s_add_u32 s34, s52, s34
	s_addc_u32 s35, s53, s35
	s_and_b64 s[38:39], s[8:9], exec
	s_cselect_b32 s11, s35, s37
	s_cselect_b32 s13, s34, s36
	s_add_u32 s14, s14, 0x40080
	s_addc_u32 s15, s15, 0
	s_add_u32 s27, s36, 0x100
	v_mov_b32_e32 v4, 0
	s_addc_u32 s29, s37, 0
	s_mov_b32 s40, -2
	s_cmp_eq_u32 s10, 32
	s_cselect_b32 s40, 12, -2
	v_mov_b32_e32 v5, v4
	v_mov_b32_e32 v6, v4
	v_mov_b32_e32 v7, v4
	v_mov_b32_e32 v8, v4
	v_mov_b32_e32 v9, v4
	v_mov_b32_e32 v10, v4
	v_mov_b32_e32 v11, v4
	v_mov_b32_e32 v20, v4
	v_mov_b32_e32 v21, v4
	v_mov_b32_e32 v22, v4
	v_mov_b32_e32 v23, v4
	v_mov_b32_e32 v24, v4
	v_mov_b32_e32 v25, v4
	v_mov_b32_e32 v26, v4
	v_mov_b32_e32 v27, v4
	v_mov_b32_e32 v36, v4
	v_mov_b32_e32 v37, v4
	v_mov_b32_e32 v38, v4
	v_mov_b32_e32 v39, v4
	v_mov_b32_e32 v40, v4
	v_mov_b32_e32 v41, v4
	v_mov_b32_e32 v42, v4
	v_mov_b32_e32 v43, v4
	v_mov_b32_e32 v52, v4
	v_mov_b32_e32 v53, v4
	v_mov_b32_e32 v54, v4
	v_mov_b32_e32 v55, v4
	v_mov_b32_e32 v56, v4
	v_mov_b32_e32 v57, v4
	v_mov_b32_e32 v58, v4
	v_mov_b32_e32 v59, v4
	v_mov_b32_e32 v12, v4
	v_mov_b32_e32 v13, v4
	v_mov_b32_e32 v14, v4
	v_mov_b32_e32 v15, v4
	v_mov_b32_e32 v16, v4
	v_mov_b32_e32 v17, v4
	v_mov_b32_e32 v18, v4
	v_mov_b32_e32 v19, v4
	v_mov_b32_e32 v28, v4
	v_mov_b32_e32 v29, v4
	v_mov_b32_e32 v30, v4
	v_mov_b32_e32 v31, v4
	v_mov_b32_e32 v32, v4
	v_mov_b32_e32 v33, v4
	v_mov_b32_e32 v34, v4
	v_mov_b32_e32 v35, v4
	v_mov_b32_e32 v44, v4
	v_mov_b32_e32 v45, v4
	v_mov_b32_e32 v46, v4
	v_mov_b32_e32 v47, v4
	v_mov_b32_e32 v48, v4
	v_mov_b32_e32 v49, v4
	v_mov_b32_e32 v50, v4
	v_mov_b32_e32 v51, v4
	v_mov_b32_e32 v60, v4
	v_mov_b32_e32 v61, v4
	v_mov_b32_e32 v62, v4
	v_mov_b32_e32 v63, v4
	v_mov_b32_e32 v64, v4
	v_mov_b32_e32 v65, v4
	v_mov_b32_e32 v66, v4
	v_mov_b32_e32 v67, v4
	v_mov_b32_e32 v68, v4
	v_mov_b32_e32 v69, v4
	v_mov_b32_e32 v70, v4
	v_mov_b32_e32 v71, v4
	v_mov_b32_e32 v72, v4
	v_mov_b32_e32 v73, v4
	v_mov_b32_e32 v74, v4
	v_mov_b32_e32 v75, v4
	v_mov_b32_e32 v84, v4
	v_mov_b32_e32 v85, v4
	v_mov_b32_e32 v86, v4
	v_mov_b32_e32 v87, v4
	v_mov_b32_e32 v88, v4
	v_mov_b32_e32 v89, v4
	v_mov_b32_e32 v90, v4
	v_mov_b32_e32 v91, v4
	v_mov_b32_e32 v100, v4
	v_mov_b32_e32 v101, v4
	v_mov_b32_e32 v102, v4
	v_mov_b32_e32 v103, v4
	v_mov_b32_e32 v104, v4
	v_mov_b32_e32 v105, v4
	v_mov_b32_e32 v106, v4
	v_mov_b32_e32 v107, v4
	v_mov_b32_e32 v116, v4
	v_mov_b32_e32 v117, v4
	v_mov_b32_e32 v118, v4
	v_mov_b32_e32 v119, v4
	s_waitcnt vmcnt(0)
	v_mov_b32_e32 v120, v4
	v_mov_b32_e32 v121, v4
	v_mov_b32_e32 v122, v4
	v_mov_b32_e32 v123, v4
	v_mov_b32_e32 v76, v4
	v_mov_b32_e32 v77, v4
	v_mov_b32_e32 v78, v4
	v_mov_b32_e32 v79, v4
	v_mov_b32_e32 v80, v4
	v_mov_b32_e32 v81, v4
	v_mov_b32_e32 v82, v4
	v_mov_b32_e32 v83, v4
	v_mov_b32_e32 v92, v4
	v_mov_b32_e32 v93, v4
	v_mov_b32_e32 v94, v4
	v_mov_b32_e32 v95, v4
	v_mov_b32_e32 v96, v4
	v_mov_b32_e32 v97, v4
	v_mov_b32_e32 v98, v4
	v_mov_b32_e32 v99, v4
	v_mov_b32_e32 v108, v4
	v_mov_b32_e32 v109, v4
	v_mov_b32_e32 v110, v4
	v_mov_b32_e32 v111, v4
	v_mov_b32_e32 v112, v4
	v_mov_b32_e32 v113, v4
	v_mov_b32_e32 v114, v4
	v_mov_b32_e32 v115, v4
	v_mov_b32_e32 v124, v4
	v_mov_b32_e32 v125, v4
	v_mov_b32_e32 v126, v4
	v_mov_b32_e32 v127, v4
	v_mov_b32_e32 v128, v4
	v_mov_b32_e32 v129, v4
	v_mov_b32_e32 v130, v4
	v_mov_b32_e32 v131, v4
	.p2align 6
	s_nop 0
	s_nop 0
	s_nop 0
	s_nop 0
	s_nop 0
	s_nop 0
	s_nop 0
	s_nop 0
	s_nop 0
	s_nop 0
	s_nop 0
	s_nop 0
	s_nop 0
	s_nop 0

; template <class Epi, class Sched, bool ALIGN_EPI = false, bool SP2 = false>
; __device__ __forceinline__ void gemm_phase(PG8_LAS unsigned char* lds, const Gemm g, const Sched& S, const Epi& E, const int tid_arg) {
;     ...
;         const bool has_next = S.next(ui + 1, nxt);
;         const char* nA = has_next ? (const char*)g.A + (size_t)nxt.pm * tstep : cA; const char* nB = has_next ? (const char*)g.Bt + (size_t)nxt.pn * tstep : cB;
;     ...
; #pragma unroll
;         for (int a = 0; a < 2; ++a)
; #pragma unroll
;             for (int b = 0; b < 2; ++b)
; #pragma unroll
;                 for (int m = 0; m < 4; ++m)
; #pragma unroll
;                     for (int n = 0; n < 2; ++n) acc[a][b][m][n] = (f32x4){0.f, 0.f, 0.f, 0.f};
;         cur = nxt; cA = nA; cB = nB; ++ui;
.LBB0_763:
	s_ashr_i32 s27, s26, 31
	s_lshl_b64 s[28:29], s[26:27], 19
	s_add_u32 s28, s3, s28
	s_addc_u32 s29, s6, s29
	s_and_b64 s[30:31], s[10:11], exec
	s_cselect_b32 s27, s29, s5
	s_cselect_b32 s48, s28, s4
	s_ashr_i32 s25, s24, 31
	s_lshl_b64 s[30:31], s[24:25], 19
	s_add_u32 s30, s7, s30
	s_addc_u32 s31, s38, s31
	s_and_b64 s[36:37], s[10:11], exec
	s_cselect_b32 s25, s31, s35
	s_cselect_b32 s49, s30, s34
	s_add_u32 s4, s4, 0x40080
	s_addc_u32 s5, s5, 0
	s_add_u32 s50, s34, 0x100
	v_mov_b32_e32 v4, 0
	s_addc_u32 s51, s35, 0
	s_mov_b32 s52, -2
	v_mov_b32_e32 v5, v4
	v_mov_b32_e32 v6, v4
	v_mov_b32_e32 v7, v4
	v_mov_b32_e32 v8, v4
	v_mov_b32_e32 v9, v4
	v_mov_b32_e32 v10, v4
	v_mov_b32_e32 v11, v4
	v_mov_b32_e32 v20, v4
	v_mov_b32_e32 v21, v4
	v_mov_b32_e32 v22, v4
	v_mov_b32_e32 v23, v4
	v_mov_b32_e32 v24, v4
	v_mov_b32_e32 v25, v4
	v_mov_b32_e32 v26, v4
	v_mov_b32_e32 v27, v4
	v_mov_b32_e32 v36, v4
	v_mov_b32_e32 v37, v4
	v_mov_b32_e32 v38, v4
	v_mov_b32_e32 v39, v4
	v_mov_b32_e32 v40, v4
	v_mov_b32_e32 v41, v4
	v_mov_b32_e32 v42, v4
	v_mov_b32_e32 v43, v4
	v_mov_b32_e32 v52, v4
	v_mov_b32_e32 v53, v4
	v_mov_b32_e32 v54, v4
	v_mov_b32_e32 v55, v4
	v_mov_b32_e32 v56, v4
	v_mov_b32_e32 v57, v4
	v_mov_b32_e32 v58, v4
	v_mov_b32_e32 v59, v4
	v_mov_b32_e32 v12, v4
	v_mov_b32_e32 v13, v4
	v_mov_b32_e32 v14, v4
	v_mov_b32_e32 v15, v4
	v_mov_b32_e32 v16, v4
	v_mov_b32_e32 v17, v4
	v_mov_b32_e32 v18, v4
	v_mov_b32_e32 v19, v4
	v_mov_b32_e32 v28, v4
	v_mov_b32_e32 v29, v4
	v_mov_b32_e32 v30, v4
	v_mov_b32_e32 v31, v4
	v_mov_b32_e32 v32, v4
	v_mov_b32_e32 v33, v4
	v_mov_b32_e32 v34, v4
	v_mov_b32_e32 v35, v4
	v_mov_b32_e32 v44, v4
	v_mov_b32_e32 v45, v4
	v_mov_b32_e32 v46, v4
	v_mov_b32_e32 v47, v4
	v_mov_b32_e32 v48, v4
	v_mov_b32_e32 v49, v4
	v_mov_b32_e32 v50, v4
	v_mov_b32_e32 v51, v4
	v_mov_b32_e32 v60, v4
	v_mov_b32_e32 v61, v4
	v_mov_b32_e32 v62, v4
	v_mov_b32_e32 v63, v4
	v_mov_b32_e32 v64, v4
	v_mov_b32_e32 v65, v4
	v_mov_b32_e32 v66, v4
	v_mov_b32_e32 v67, v4
	v_mov_b32_e32 v68, v4
	v_mov_b32_e32 v69, v4
	v_mov_b32_e32 v70, v4
	v_mov_b32_e32 v71, v4
	v_mov_b32_e32 v72, v4
	v_mov_b32_e32 v73, v4
	v_mov_b32_e32 v74, v4
	v_mov_b32_e32 v75, v4
	v_mov_b32_e32 v84, v4
	v_mov_b32_e32 v85, v4
	v_mov_b32_e32 v86, v4
	v_mov_b32_e32 v87, v4
	v_mov_b32_e32 v88, v4
	v_mov_b32_e32 v89, v4
	v_mov_b32_e32 v90, v4
	v_mov_b32_e32 v91, v4
	v_mov_b32_e32 v100, v4
	v_mov_b32_e32 v101, v4
	v_mov_b32_e32 v102, v4
	v_mov_b32_e32 v103, v4
	v_mov_b32_e32 v104, v4
	v_mov_b32_e32 v105, v4
	v_mov_b32_e32 v106, v4
	v_mov_b32_e32 v107, v4
	v_mov_b32_e32 v116, v4
	v_mov_b32_e32 v117, v4
	v_mov_b32_e32 v118, v4
	v_mov_b32_e32 v119, v4
	s_waitcnt vmcnt(0)
	v_mov_b32_e32 v120, v4
	v_mov_b32_e32 v121, v4
	v_mov_b32_e32 v122, v4
	v_mov_b32_e32 v123, v4
	v_mov_b32_e32 v76, v4
	v_mov_b32_e32 v77, v4
	v_mov_b32_e32 v78, v4
	v_mov_b32_e32 v79, v4
	v_mov_b32_e32 v80, v4
	v_mov_b32_e32 v81, v4
	v_mov_b32_e32 v82, v4
	v_mov_b32_e32 v83, v4
	v_mov_b32_e32 v92, v4
	v_mov_b32_e32 v93, v4
	v_mov_b32_e32 v94, v4
	v_mov_b32_e32 v95, v4
	v_mov_b32_e32 v96, v4
	v_mov_b32_e32 v97, v4
	v_mov_b32_e32 v98, v4
	v_mov_b32_e32 v99, v4
	v_mov_b32_e32 v108, v4
	v_mov_b32_e32 v109, v4
	v_mov_b32_e32 v110, v4
	v_mov_b32_e32 v111, v4
	v_mov_b32_e32 v112, v4
	v_mov_b32_e32 v113, v4
	v_mov_b32_e32 v114, v4
	v_mov_b32_e32 v115, v4
	v_mov_b32_e32 v124, v4
	v_mov_b32_e32 v125, v4
	v_mov_b32_e32 v126, v4
	v_mov_b32_e32 v127, v4
	v_mov_b32_e32 v128, v4
	v_mov_b32_e32 v129, v4
	v_mov_b32_e32 v130, v4
	v_mov_b32_e32 v131, v4
	.p2align 6
	s_nop 0
	s_nop 0
	s_nop 0
	s_nop 0
	s_nop 0
	s_nop 0

; template <class Epi, class Sched, bool ALIGN_EPI = false, bool SP2 = false>
; __device__ __forceinline__ void gemm_phase(PG8_LAS unsigned char* lds, const Gemm g, const Sched& S, const Epi& E, const int tid_arg) {
;     ...
;         const bool has_next = S.next(ui + 1, nxt);
;         const char* nA = has_next ? (const char*)g.A + (size_t)nxt.pm * tstep : cA; const char* nB = has_next ? (const char*)g.Bt + (size_t)nxt.pn * tstep : cB;
;     ...
; #pragma unroll
;         for (int a = 0; a < 2; ++a)
; #pragma unroll
;             for (int b = 0; b < 2; ++b)
; #pragma unroll
;                 for (int m = 0; m < 4; ++m)
; #pragma unroll
;                     for (int n = 0; n < 2; ++n) acc[a][b][m][n] = (f32x4){0.f, 0.f, 0.f, 0.f};
;         cur = nxt; cA = nA; cB = nB; ++ui;
.LBB0_789:
	s_ashr_i32 s27, s26, 31
	s_lshl_b64 s[28:29], s[26:27], 19
	s_add_u32 s28, s40, s28
	s_addc_u32 s29, s41, s29
	s_and_b64 s[30:31], s[10:11], exec
	s_cselect_b32 s27, s29, s35
	s_cselect_b32 s52, s28, s34
	s_ashr_i32 s25, s24, 31
	s_lshl_b64 s[30:31], s[24:25], 19
	s_add_u32 s30, s42, s30
	s_addc_u32 s31, s43, s31
	s_and_b64 s[38:39], s[10:11], exec
	s_cselect_b32 s25, s31, s37
	s_cselect_b32 s53, s30, s36
	s_add_u32 s34, s34, 0x40080
	s_addc_u32 s35, s35, 0
	s_add_u32 s54, s36, 0x100
	v_mov_b32_e32 v4, 0
	s_addc_u32 s55, s37, 0
	s_mov_b32 s56, -2
	v_mov_b32_e32 v5, v4
	v_mov_b32_e32 v6, v4
	v_mov_b32_e32 v7, v4
	v_mov_b32_e32 v8, v4
	v_mov_b32_e32 v9, v4
	v_mov_b32_e32 v10, v4
	v_mov_b32_e32 v11, v4
	v_mov_b32_e32 v20, v4
	v_mov_b32_e32 v21, v4
	v_mov_b32_e32 v22, v4
	v_mov_b32_e32 v23, v4
	v_mov_b32_e32 v24, v4
	v_mov_b32_e32 v25, v4
	v_mov_b32_e32 v26, v4
	v_mov_b32_e32 v27, v4
	v_mov_b32_e32 v36, v4
	v_mov_b32_e32 v37, v4
	v_mov_b32_e32 v38, v4
	v_mov_b32_e32 v39, v4
	v_mov_b32_e32 v40, v4
	v_mov_b32_e32 v41, v4
	v_mov_b32_e32 v42, v4
	v_mov_b32_e32 v43, v4
	v_mov_b32_e32 v52, v4
	v_mov_b32_e32 v53, v4
	v_mov_b32_e32 v54, v4
	v_mov_b32_e32 v55, v4
	v_mov_b32_e32 v56, v4
	v_mov_b32_e32 v57, v4
	v_mov_b32_e32 v58, v4
	v_mov_b32_e32 v59, v4
	v_mov_b32_e32 v12, v4
	v_mov_b32_e32 v13, v4
	v_mov_b32_e32 v14, v4
	v_mov_b32_e32 v15, v4
	v_mov_b32_e32 v16, v4
	v_mov_b32_e32 v17, v4
	v_mov_b32_e32 v18, v4
	v_mov_b32_e32 v19, v4
	v_mov_b32_e32 v28, v4
	v_mov_b32_e32 v29, v4
	v_mov_b32_e32 v30, v4
	v_mov_b32_e32 v31, v4
	v_mov_b32_e32 v32, v4
	v_mov_b32_e32 v33, v4
	v_mov_b32_e32 v34, v4
	v_mov_b32_e32 v35, v4
	v_mov_b32_e32 v44, v4
	v_mov_b32_e32 v45, v4
	v_mov_b32_e32 v46, v4
	v_mov_b32_e32 v47, v4
	v_mov_b32_e32 v48, v4
	v_mov_b32_e32 v49, v4
	v_mov_b32_e32 v50, v4
	v_mov_b32_e32 v51, v4
	v_mov_b32_e32 v60, v4
	v_mov_b32_e32 v61, v4
	v_mov_b32_e32 v62, v4
	v_mov_b32_e32 v63, v4
	v_mov_b32_e32 v64, v4
	v_mov_b32_e32 v65, v4
	v_mov_b32_e32 v66, v4
	v_mov_b32_e32 v67, v4
	v_mov_b32_e32 v68, v4
	v_mov_b32_e32 v69, v4
	v_mov_b32_e32 v70, v4
	v_mov_b32_e32 v71, v4
	v_mov_b32_e32 v72, v4
	v_mov_b32_e32 v73, v4
	v_mov_b32_e32 v74, v4
	v_mov_b32_e32 v75, v4
	v_mov_b32_e32 v84, v4
	v_mov_b32_e32 v85, v4
	v_mov_b32_e32 v86, v4
	v_mov_b32_e32 v87, v4
	v_mov_b32_e32 v88, v4
	v_mov_b32_e32 v89, v4
	v_mov_b32_e32 v90, v4
	v_mov_b32_e32 v91, v4
	v_mov_b32_e32 v100, v4
	v_mov_b32_e32 v101, v4
	v_mov_b32_e32 v102, v4
	v_mov_b32_e32 v103, v4
	v_mov_b32_e32 v104, v4
	v_mov_b32_e32 v105, v4
	v_mov_b32_e32 v106, v4
	v_mov_b32_e32 v107, v4
	v_mov_b32_e32 v116, v4
	v_mov_b32_e32 v117, v4
	v_mov_b32_e32 v118, v4
	v_mov_b32_e32 v119, v4
	s_waitcnt vmcnt(0)
	v_mov_b32_e32 v120, v4
	v_mov_b32_e32 v121, v4
	v_mov_b32_e32 v122, v4
	v_mov_b32_e32 v123, v4
	v_mov_b32_e32 v76, v4
	v_mov_b32_e32 v77, v4
	v_mov_b32_e32 v78, v4
	v_mov_b32_e32 v79, v4
	v_mov_b32_e32 v80, v4
	v_mov_b32_e32 v81, v4
	v_mov_b32_e32 v82, v4
	v_mov_b32_e32 v83, v4
	v_mov_b32_e32 v92, v4
	v_mov_b32_e32 v93, v4
	v_mov_b32_e32 v94, v4
	v_mov_b32_e32 v95, v4
	v_mov_b32_e32 v96, v4
	v_mov_b32_e32 v97, v4
	v_mov_b32_e32 v98, v4
	v_mov_b32_e32 v99, v4
	v_mov_b32_e32 v108, v4
	v_mov_b32_e32 v109, v4
	v_mov_b32_e32 v110, v4
	v_mov_b32_e32 v111, v4
	v_mov_b32_e32 v112, v4
	v_mov_b32_e32 v113, v4
	v_mov_b32_e32 v114, v4
	v_mov_b32_e32 v115, v4
	v_mov_b32_e32 v124, v4
	v_mov_b32_e32 v125, v4
	v_mov_b32_e32 v126, v4
	v_mov_b32_e32 v127, v4
	v_mov_b32_e32 v128, v4
	v_mov_b32_e32 v129, v4
	v_mov_b32_e32 v130, v4
	v_mov_b32_e32 v131, v4
	.p2align 6
	s_nop 0

; template <class Epi, class Sched, bool ALIGN_EPI = false, bool SP2 = false>
; __device__ __forceinline__ void gemm_phase(PG8_LAS unsigned char* lds, const Gemm g, const Sched& S, const Epi& E, const int tid_arg) {
;     ...
;         const bool has_next = S.next(ui + 1, nxt);
;         const char* nA = has_next ? (const char*)g.A + (size_t)nxt.pm * tstep : cA; const char* nB = has_next ? (const char*)g.Bt + (size_t)nxt.pn * tstep : cB;
;     ...
; #pragma unroll
;         for (int a = 0; a < 2; ++a)
; #pragma unroll
;             for (int b = 0; b < 2; ++b)
; #pragma unroll
;                 for (int m = 0; m < 4; ++m)
; #pragma unroll
;                     for (int n = 0; n < 2; ++n) acc[a][b][m][n] = (f32x4){0.f, 0.f, 0.f, 0.f};
;         cur = nxt; cA = nA; cB = nB; ++ui;
.LBB0_867:
	s_ashr_i32 s35, s34, 31
	s_lshl_b64 s[36:37], s[34:35], 19
	s_add_u32 s36, s2, s36
	s_addc_u32 s37, s47, s37
	s_and_b64 s[38:39], s[14:15], exec
	s_cselect_b32 s7, s37, s17
	s_cselect_b32 s35, s36, s16
	s_ashr_i32 s31, s30, 31
	s_lshl_b64 s[38:39], s[30:31], 19
	s_add_u32 s38, s48, s38
	s_addc_u32 s39, s49, s39
	s_and_b64 s[44:45], s[14:15], exec
	s_cselect_b32 s31, s39, s43
	s_cselect_b32 s41, s38, s42
	s_add_u32 s16, s16, 0x40080
	s_addc_u32 s17, s17, 0
	s_add_u32 s59, s42, 0x100
	v_mov_b32_e32 v4, 0
	s_addc_u32 s60, s43, 0
	s_mov_b32 s61, -2
	s_waitcnt lgkmcnt(0)
	v_mov_b32_e32 v5, v4
	v_mov_b32_e32 v6, v4
	v_mov_b32_e32 v7, v4
	v_mov_b32_e32 v8, v4
	v_mov_b32_e32 v9, v4
	v_mov_b32_e32 v10, v4
	v_mov_b32_e32 v11, v4
	v_mov_b32_e32 v20, v4
	v_mov_b32_e32 v21, v4
	v_mov_b32_e32 v22, v4
	v_mov_b32_e32 v23, v4
	v_mov_b32_e32 v24, v4
	v_mov_b32_e32 v25, v4
	v_mov_b32_e32 v26, v4
	v_mov_b32_e32 v27, v4
	v_mov_b32_e32 v36, v4
	v_mov_b32_e32 v37, v4
	v_mov_b32_e32 v38, v4
	v_mov_b32_e32 v39, v4
	v_mov_b32_e32 v40, v4
	v_mov_b32_e32 v41, v4
	v_mov_b32_e32 v42, v4
	v_mov_b32_e32 v43, v4
	v_mov_b32_e32 v52, v4
	v_mov_b32_e32 v53, v4
	v_mov_b32_e32 v54, v4
	v_mov_b32_e32 v55, v4
	v_mov_b32_e32 v56, v4
	v_mov_b32_e32 v57, v4
	v_mov_b32_e32 v58, v4
	v_mov_b32_e32 v59, v4
	v_mov_b32_e32 v12, v4
	v_mov_b32_e32 v13, v4
	v_mov_b32_e32 v14, v4
	v_mov_b32_e32 v15, v4
	v_mov_b32_e32 v16, v4
	v_mov_b32_e32 v17, v4
	v_mov_b32_e32 v18, v4
	v_mov_b32_e32 v19, v4
	v_mov_b32_e32 v28, v4
	v_mov_b32_e32 v29, v4
	v_mov_b32_e32 v30, v4
	v_mov_b32_e32 v31, v4
	v_mov_b32_e32 v32, v4
	v_mov_b32_e32 v33, v4
	v_mov_b32_e32 v34, v4
	v_mov_b32_e32 v35, v4
	v_mov_b32_e32 v44, v4
	v_mov_b32_e32 v45, v4
	v_mov_b32_e32 v46, v4
	v_mov_b32_e32 v47, v4
	v_mov_b32_e32 v48, v4
	v_mov_b32_e32 v49, v4
	v_mov_b32_e32 v50, v4
	v_mov_b32_e32 v51, v4
	v_mov_b32_e32 v60, v4
	v_mov_b32_e32 v61, v4
	v_mov_b32_e32 v62, v4
	v_mov_b32_e32 v63, v4
	v_mov_b32_e32 v64, v4
	v_mov_b32_e32 v65, v4
	v_mov_b32_e32 v66, v4
	v_mov_b32_e32 v67, v4
	v_mov_b32_e32 v68, v4
	v_mov_b32_e32 v69, v4
	v_mov_b32_e32 v70, v4
	v_mov_b32_e32 v71, v4
	v_mov_b32_e32 v72, v4
	v_mov_b32_e32 v73, v4
	v_mov_b32_e32 v74, v4
	v_mov_b32_e32 v75, v4
	v_mov_b32_e32 v84, v4
	v_mov_b32_e32 v85, v4
	v_mov_b32_e32 v86, v4
	v_mov_b32_e32 v87, v4
	v_mov_b32_e32 v88, v4
	v_mov_b32_e32 v89, v4
	v_mov_b32_e32 v90, v4
	v_mov_b32_e32 v91, v4
	v_mov_b32_e32 v100, v4
	v_mov_b32_e32 v101, v4
	v_mov_b32_e32 v102, v4
	v_mov_b32_e32 v103, v4
	v_mov_b32_e32 v104, v4
	v_mov_b32_e32 v105, v4
	v_mov_b32_e32 v106, v4
	v_mov_b32_e32 v107, v4
	v_mov_b32_e32 v116, v4
	v_mov_b32_e32 v117, v4
	v_mov_b32_e32 v118, v4
	v_mov_b32_e32 v119, v4
	s_waitcnt vmcnt(0)
	v_mov_b32_e32 v120, v4
	v_mov_b32_e32 v121, v4
	v_mov_b32_e32 v122, v4
	v_mov_b32_e32 v123, v4
	v_mov_b32_e32 v76, v4
	v_mov_b32_e32 v77, v4
	v_mov_b32_e32 v78, v4
	v_mov_b32_e32 v79, v4
	v_mov_b32_e32 v80, v4
	v_mov_b32_e32 v81, v4
	v_mov_b32_e32 v82, v4
	v_mov_b32_e32 v83, v4
	v_mov_b32_e32 v92, v4
	v_mov_b32_e32 v93, v4
	v_mov_b32_e32 v94, v4
	v_mov_b32_e32 v95, v4
	v_mov_b32_e32 v96, v4
	v_mov_b32_e32 v97, v4
	v_mov_b32_e32 v98, v4
	v_mov_b32_e32 v99, v4
	v_mov_b32_e32 v108, v4
	v_mov_b32_e32 v109, v4
	v_mov_b32_e32 v110, v4
	v_mov_b32_e32 v111, v4
	v_mov_b32_e32 v112, v4
	v_mov_b32_e32 v113, v4
	v_mov_b32_e32 v114, v4
	v_mov_b32_e32 v115, v4
	v_mov_b32_e32 v124, v4
	v_mov_b32_e32 v125, v4
	v_mov_b32_e32 v126, v4
	v_mov_b32_e32 v127, v4
	v_mov_b32_e32 v128, v4
	v_mov_b32_e32 v129, v4
	v_mov_b32_e32 v130, v4
	v_mov_b32_e32 v131, v4
	.p2align 6
	s_nop 0
	s_nop 0
	s_nop 0
	s_nop 0
	s_nop 0
	s_nop 0
	s_nop 0
	s_nop 0
	s_nop 0
	s_nop 0
	s_nop 0

; template <class Epi, class Sched, bool ALIGN_EPI = false, bool SP2 = false>
; __device__ __forceinline__ void gemm_phase(PG8_LAS unsigned char* lds, const Gemm g, const Sched& S, const Epi& E, const int tid_arg) {
;     ...
;         const bool has_next = S.next(ui + 1, nxt);
;         const char* nA = has_next ? (const char*)g.A + (size_t)nxt.pm * tstep : cA; const char* nB = has_next ? (const char*)g.Bt + (size_t)nxt.pn * tstep : cB;
;     ...
; #pragma unroll
;         for (int a = 0; a < 2; ++a)
; #pragma unroll
;             for (int b = 0; b < 2; ++b)
; #pragma unroll
;                 for (int m = 0; m < 4; ++m)
; #pragma unroll
;                     for (int n = 0; n < 2; ++n) acc[a][b][m][n] = (f32x4){0.f, 0.f, 0.f, 0.f};
;         cur = nxt; cA = nA; cB = nB; ++ui;
.LBB0_1079:
	s_ashr_i32 s21, s20, 31
	s_lshl_b64 s[22:23], s[20:21], 19
	s_add_u32 s22, s0, s22
	s_addc_u32 s23, s1, s23
	s_and_b64 s[24:25], s[10:11], exec
	s_cselect_b32 s21, s23, s29
	s_cselect_b32 s47, s22, s28
	s_ashr_i32 s17, s16, 31
	s_lshl_b64 s[24:25], s[16:17], 19
	s_add_u32 s24, s2, s24
	s_addc_u32 s25, s3, s25
	s_and_b64 s[34:35], s[10:11], exec
	s_cselect_b32 s17, s25, s31
	s_cselect_b32 s48, s24, s30
	s_add_u32 s28, s28, 0x40080
	s_addc_u32 s29, s29, 0
	s_add_u32 s49, s30, 0x100
	v_mov_b32_e32 v2, 0
	s_addc_u32 s50, s31, 0
	s_mov_b32 s51, -2
	v_mov_b32_e32 v3, v2
	v_mov_b32_e32 v4, v2
	v_mov_b32_e32 v5, v2
	v_mov_b32_e32 v6, v2
	v_mov_b32_e32 v7, v2
	v_mov_b32_e32 v8, v2
	v_mov_b32_e32 v9, v2
	v_mov_b32_e32 v18, v2
	v_mov_b32_e32 v19, v2
	v_mov_b32_e32 v20, v2
	v_mov_b32_e32 v21, v2
	v_mov_b32_e32 v22, v2
	v_mov_b32_e32 v23, v2
	v_mov_b32_e32 v24, v2
	v_mov_b32_e32 v25, v2
	v_mov_b32_e32 v34, v2
	v_mov_b32_e32 v35, v2
	v_mov_b32_e32 v36, v2
	v_mov_b32_e32 v37, v2
	v_mov_b32_e32 v38, v2
	v_mov_b32_e32 v39, v2
	v_mov_b32_e32 v40, v2
	v_mov_b32_e32 v41, v2
	v_mov_b32_e32 v50, v2
	v_mov_b32_e32 v51, v2
	v_mov_b32_e32 v52, v2
	v_mov_b32_e32 v53, v2
	v_mov_b32_e32 v54, v2
	v_mov_b32_e32 v55, v2
	v_mov_b32_e32 v56, v2
	v_mov_b32_e32 v57, v2
	v_mov_b32_e32 v10, v2
	v_mov_b32_e32 v11, v2
	v_mov_b32_e32 v12, v2
	v_mov_b32_e32 v13, v2
	v_mov_b32_e32 v14, v2
	v_mov_b32_e32 v15, v2
	v_mov_b32_e32 v16, v2
	v_mov_b32_e32 v17, v2
	v_mov_b32_e32 v26, v2
	v_mov_b32_e32 v27, v2
	v_mov_b32_e32 v28, v2
	v_mov_b32_e32 v29, v2
	v_mov_b32_e32 v30, v2
	v_mov_b32_e32 v31, v2
	v_mov_b32_e32 v32, v2
	v_mov_b32_e32 v33, v2
	v_mov_b32_e32 v42, v2
	v_mov_b32_e32 v43, v2
	v_mov_b32_e32 v44, v2
	v_mov_b32_e32 v45, v2
	v_mov_b32_e32 v46, v2
	v_mov_b32_e32 v47, v2
	v_mov_b32_e32 v48, v2
	v_mov_b32_e32 v49, v2
	v_mov_b32_e32 v58, v2
	v_mov_b32_e32 v59, v2
	v_mov_b32_e32 v60, v2
	v_mov_b32_e32 v61, v2
	v_mov_b32_e32 v62, v2
	v_mov_b32_e32 v63, v2
	v_mov_b32_e32 v64, v2
	v_mov_b32_e32 v65, v2
	v_mov_b32_e32 v66, v2
	v_mov_b32_e32 v67, v2
	v_mov_b32_e32 v68, v2
	v_mov_b32_e32 v69, v2
	v_mov_b32_e32 v70, v2
	v_mov_b32_e32 v71, v2
	v_mov_b32_e32 v72, v2
	v_mov_b32_e32 v73, v2
	v_mov_b32_e32 v82, v2
	v_mov_b32_e32 v83, v2
	v_mov_b32_e32 v84, v2
	v_mov_b32_e32 v85, v2
	v_mov_b32_e32 v86, v2
	v_mov_b32_e32 v87, v2
	v_mov_b32_e32 v88, v2
	v_mov_b32_e32 v89, v2
	v_mov_b32_e32 v98, v2
	v_mov_b32_e32 v99, v2
	v_mov_b32_e32 v100, v2
	v_mov_b32_e32 v101, v2
	v_mov_b32_e32 v102, v2
	v_mov_b32_e32 v103, v2
	v_mov_b32_e32 v104, v2
	v_mov_b32_e32 v105, v2
	v_mov_b32_e32 v114, v2
	v_mov_b32_e32 v115, v2
	v_mov_b32_e32 v116, v2
	v_mov_b32_e32 v117, v2
	v_mov_b32_e32 v118, v2
	v_mov_b32_e32 v119, v2
	v_mov_b32_e32 v120, v2
	v_mov_b32_e32 v121, v2
	v_mov_b32_e32 v74, v2
	v_mov_b32_e32 v75, v2
	v_mov_b32_e32 v76, v2
	v_mov_b32_e32 v77, v2
	v_mov_b32_e32 v78, v2
	v_mov_b32_e32 v79, v2
	v_mov_b32_e32 v80, v2
	v_mov_b32_e32 v81, v2
	v_mov_b32_e32 v90, v2
	v_mov_b32_e32 v91, v2
	v_mov_b32_e32 v92, v2
	v_mov_b32_e32 v93, v2
	v_mov_b32_e32 v94, v2
	v_mov_b32_e32 v95, v2
	v_mov_b32_e32 v96, v2
	v_mov_b32_e32 v97, v2
	v_mov_b32_e32 v106, v2
	v_mov_b32_e32 v107, v2
	v_mov_b32_e32 v108, v2
	v_mov_b32_e32 v109, v2
	v_mov_b32_e32 v110, v2
	v_mov_b32_e32 v111, v2
	v_mov_b32_e32 v112, v2
	v_mov_b32_e32 v113, v2
	v_mov_b32_e32 v122, v2
	v_mov_b32_e32 v123, v2
	v_mov_b32_e32 v124, v2
	v_mov_b32_e32 v125, v2
	v_mov_b32_e32 v126, v2
	v_mov_b32_e32 v127, v2
	v_mov_b32_e32 v128, v2
	v_mov_b32_e32 v129, v2
	.p2align 6
	s_nop 0
	s_nop 0
	s_nop 0
	s_nop 0
	s_nop 0

; template <class Epi, class Sched, bool ALIGN_EPI = false, bool SP2 = false>
; __device__ __forceinline__ void gemm_phase(PG8_LAS unsigned char* lds, const Gemm g, const Sched& S, const Epi& E, const int tid_arg) {
;     ...
; #pragma unroll
;         for (int a = 0; a < 2; ++a)
; #pragma unroll
;             for (int b = 0; b < 2; ++b)
; #pragma unroll
;                 for (int m = 0; m < 4; ++m)
; #pragma unroll
;                     for (int n = 0; n < 2; ++n) acc[a][b][m][n] = (f32x4){0.f, 0.f, 0.f, 0.f};
;         cur = nxt; cA = nA; cB = nB; ++ui;
.LBB0_1169:
	s_add_u32 s23, s26, 0x100
	v_mov_b32_e32 v0, 0
	s_addc_u32 s46, s27, 0
	s_mov_b32 s47, -2
	v_mov_b32_e32 v1, v0
	v_mov_b32_e32 v2, v0
	v_mov_b32_e32 v3, v0
	v_mov_b32_e32 v4, v0
	v_mov_b32_e32 v5, v0
	v_mov_b32_e32 v6, v0
	v_mov_b32_e32 v7, v0
	v_mov_b32_e32 v16, v0
	v_mov_b32_e32 v17, v0
	v_mov_b32_e32 v18, v0
	v_mov_b32_e32 v19, v0
	v_mov_b32_e32 v20, v0
	v_mov_b32_e32 v21, v0
	v_mov_b32_e32 v22, v0
	v_mov_b32_e32 v23, v0
	v_mov_b32_e32 v32, v0
	v_mov_b32_e32 v33, v0
	v_mov_b32_e32 v34, v0
	v_mov_b32_e32 v35, v0
	v_mov_b32_e32 v36, v0
	v_mov_b32_e32 v37, v0
	v_mov_b32_e32 v38, v0
	v_mov_b32_e32 v39, v0
	v_mov_b32_e32 v48, v0
	v_mov_b32_e32 v49, v0
	v_mov_b32_e32 v50, v0
	v_mov_b32_e32 v51, v0
	v_mov_b32_e32 v52, v0
	v_mov_b32_e32 v53, v0
	v_mov_b32_e32 v54, v0
	v_mov_b32_e32 v55, v0
	v_mov_b32_e32 v8, v0
	v_mov_b32_e32 v9, v0
	v_mov_b32_e32 v10, v0
	v_mov_b32_e32 v11, v0
	v_mov_b32_e32 v12, v0
	v_mov_b32_e32 v13, v0
	v_mov_b32_e32 v14, v0
	v_mov_b32_e32 v15, v0
	v_mov_b32_e32 v24, v0
	v_mov_b32_e32 v25, v0
	v_mov_b32_e32 v26, v0
	v_mov_b32_e32 v27, v0
	v_mov_b32_e32 v28, v0
	v_mov_b32_e32 v29, v0
	v_mov_b32_e32 v30, v0
	v_mov_b32_e32 v31, v0
	v_mov_b32_e32 v40, v0
	v_mov_b32_e32 v41, v0
	v_mov_b32_e32 v42, v0
	v_mov_b32_e32 v43, v0
	v_mov_b32_e32 v44, v0
	v_mov_b32_e32 v45, v0
	v_mov_b32_e32 v46, v0
	v_mov_b32_e32 v47, v0
	v_mov_b32_e32 v56, v0
	v_mov_b32_e32 v57, v0
	v_mov_b32_e32 v58, v0
	v_mov_b32_e32 v59, v0
	v_mov_b32_e32 v60, v0
	v_mov_b32_e32 v61, v0
	v_mov_b32_e32 v62, v0
	v_mov_b32_e32 v63, v0
	v_mov_b32_e32 v64, v0
	v_mov_b32_e32 v65, v0
	v_mov_b32_e32 v66, v0
	v_mov_b32_e32 v67, v0
	v_mov_b32_e32 v68, v0
	v_mov_b32_e32 v69, v0
	v_mov_b32_e32 v70, v0
	v_mov_b32_e32 v71, v0
	v_mov_b32_e32 v80, v0
	v_mov_b32_e32 v81, v0
	v_mov_b32_e32 v82, v0
	v_mov_b32_e32 v83, v0
	v_mov_b32_e32 v84, v0
	v_mov_b32_e32 v85, v0
	v_mov_b32_e32 v86, v0
	v_mov_b32_e32 v87, v0
	v_mov_b32_e32 v96, v0
	v_mov_b32_e32 v97, v0
	v_mov_b32_e32 v98, v0
	v_mov_b32_e32 v99, v0
	v_mov_b32_e32 v100, v0
	v_mov_b32_e32 v101, v0
	v_mov_b32_e32 v102, v0
	v_mov_b32_e32 v103, v0
	v_mov_b32_e32 v112, v0
	v_mov_b32_e32 v113, v0
	v_mov_b32_e32 v114, v0
	v_mov_b32_e32 v115, v0
	v_mov_b32_e32 v116, v0
	v_mov_b32_e32 v117, v0
	v_mov_b32_e32 v118, v0
	v_mov_b32_e32 v119, v0
	v_mov_b32_e32 v72, v0
	v_mov_b32_e32 v73, v0
	v_mov_b32_e32 v74, v0
	v_mov_b32_e32 v75, v0
	v_mov_b32_e32 v76, v0
	v_mov_b32_e32 v77, v0
	v_mov_b32_e32 v78, v0
	v_mov_b32_e32 v79, v0
	v_mov_b32_e32 v88, v0
	v_mov_b32_e32 v89, v0
	v_mov_b32_e32 v90, v0
	v_mov_b32_e32 v91, v0
	v_mov_b32_e32 v92, v0
	v_mov_b32_e32 v93, v0
	v_mov_b32_e32 v94, v0
	v_mov_b32_e32 v95, v0
	v_mov_b32_e32 v104, v0
	v_mov_b32_e32 v105, v0
	v_mov_b32_e32 v106, v0
	v_mov_b32_e32 v107, v0
	v_mov_b32_e32 v108, v0
	v_mov_b32_e32 v109, v0
	v_mov_b32_e32 v110, v0
	v_mov_b32_e32 v111, v0
	v_mov_b32_e32 v120, v0
	v_mov_b32_e32 v121, v0
	v_mov_b32_e32 v122, v0
	v_mov_b32_e32 v123, v0
	v_mov_b32_e32 v124, v0
	v_mov_b32_e32 v125, v0
	v_mov_b32_e32 v126, v0
	v_mov_b32_e32 v127, v0
	.p2align 6
	s_nop 0
	s_nop 0
	s_nop 0
	s_nop 0
	s_nop 0
	s_nop 0
	s_nop 0
